# v10 + w_in EpiGen head: 8 serialized rsqrt(ssq) load/bpermute chains batched into one block (8 loads in flight)
# speedup vs baseline: 1.0326x; 1.0074x over previous
; __device__ __forceinline__ float row_ssq(const float* part, int pitch, int n4, int row, int fq) {
;     f32x4 v = (f32x4){0.f, 0.f, 0.f, 0.f};
;     if (fq < n4) v = *(const f32x4*)(part + (size_t)row * pitch + 4 * fq);
;     float s = (v[0] + v[1]) + (v[2] + v[3]);
;     s += __shfl_xor(s, 16); s += __shfl_xor(s, 32);
;     return s;
; }
;     __device__ __forceinline__ void operator()(const f32x4 (&acc)[2][2][4][2], const Unit& u, int wr, int wc, int fr, int fq) const {
;         const int row0 = u.pm * BM + wr * 64 + fr;
;         float rsv[2][4];
; #pragma unroll
;         for (int ai = 0; ai < 2; ++ai)
; #pragma unroll
;             for (int m = 0; m < 4; ++m) rsv[ai][m] = ssq_in ? rsqrtf(row_ssq(ssq_in, in_pitch, in_n4, row0 + ai * HALF + m * 16, fq) * inv_k + EPS) : 1.f;
; #pragma unroll
;         for (int bj = 0; bj < 2; ++bj) {
;             const int c0 = u.pn * BM + bj * HALF + wc * 32;
;             float scale = 1.f; bool sig = false, rp = false, st = true; float* sq = nullptr; int sqp = 0;
;             if (mode == 1) { const int slab = c0 >> 7;
;                 if (slab < 3) { sq = ssq_q + 4 * slab + wc; sqp = 16; } else if (slab < 5) { sq = ssq_kv + 4 * (slab - 3) + wc; sqp = 8; } else if (slab == 5) { rp = (wc == 0); st = (wc == 0); }
;                 else if (slab < 14) scale = C2_64; else if (slab < 18) {} else if (slab < 26) scale = C2_64; else if (slab < 42) {} else sig = true;
.LBB0_331:
	v_readlane_b32 s0, v252, 23
	v_readlane_b32 s1, v252, 24
	v_lshl_add_u32 v156, s4, 8, v139
	v_mov_b32_e32 v163, 1.0
	v_cndmask_b32_e64 v0, 0, 1, s[0:1]
	v_cmp_ne_u32_e64 s[50:51], 1, v0
	s_andn2_b64 vcc, exec, s[0:1]
	v_ashrrev_i32_e32 v157, 31, v156
	v_mov_b32_e32 v164, 1.0
	v_mov_b32_e32 v162, 1.0
	v_mov_b32_e32 v161, 1.0
	v_mov_b32_e32 v160, 1.0
	v_mov_b32_e32 v155, 1.0
	v_mov_b32_e32 v153, 1.0
	v_mov_b32_e32 v151, 1.0
	v_or_b32_e32 v154, 16, v156
	v_or_b32_e32 v152, 32, v156
	v_or_b32_e32 v150, 48, v156
	v_add_u32_e32 v148, 0x80, v156
	v_ashrrev_i32_e32 v149, 31, v148
	s_cbranch_vccnz .Lrsv_win_done
	v_lshlrev_b64 v[166:167], 6, v[156:157]
	v_lshl_add_u64 v[166:167], v[140:141], 0, v[166:167]
	global_load_dwordx4 v[168:171], v[166:167], off
	global_load_dwordx4 v[172:175], v[166:167], off offset:1024
	global_load_dwordx4 v[176:179], v[166:167], off offset:2048
	global_load_dwordx4 v[180:183], v[166:167], off offset:3072
	v_add_co_u32_e32 v166, vcc, 0x2000, v166
	v_and_b32_e32 v202, 64, v241
	v_xor_b32_e32 v200, 16, v241
	v_addc_co_u32_e32 v167, vcc, 0, v167, vcc
	global_load_dwordx4 v[184:187], v[166:167], off
	global_load_dwordx4 v[188:191], v[166:167], off offset:1024
	global_load_dwordx4 v[192:195], v[166:167], off offset:2048
	global_load_dwordx4 v[196:199], v[166:167], off offset:3072
	v_add_u32_e32 v202, 64, v202
	v_cmp_lt_i32_e32 vcc, v200, v202
	v_xor_b32_e32 v201, 32, v241
	s_nop 0
	v_cndmask_b32_e32 v200, v241, v200, vcc
	v_cmp_lt_i32_e32 vcc, v201, v202
	v_lshlrev_b32_e32 v200, 2, v200
	s_nop 0
	v_cndmask_b32_e32 v201, v241, v201, vcc
	v_lshlrev_b32_e32 v201, 2, v201
	s_waitcnt vmcnt(7)
	v_add_f32_e32 v168, v168, v169
	v_add_f32_e32 v170, v170, v171
	v_add_f32_e32 v168, v168, v170
	ds_bpermute_b32 v169, v200, v168
	s_waitcnt vmcnt(6)
	v_add_f32_e32 v172, v172, v173
	v_add_f32_e32 v174, v174, v175
	v_add_f32_e32 v172, v172, v174
	ds_bpermute_b32 v173, v200, v172
	s_waitcnt vmcnt(5)
	v_add_f32_e32 v176, v176, v177
	v_add_f32_e32 v178, v178, v179
	v_add_f32_e32 v176, v176, v178
	ds_bpermute_b32 v177, v200, v176
	s_waitcnt vmcnt(4)
	v_add_f32_e32 v180, v180, v181
	v_add_f32_e32 v182, v182, v183
	v_add_f32_e32 v180, v180, v182
	ds_bpermute_b32 v181, v200, v180
	s_waitcnt vmcnt(3)
	v_add_f32_e32 v184, v184, v185
	v_add_f32_e32 v186, v186, v187
	v_add_f32_e32 v184, v184, v186
	ds_bpermute_b32 v185, v200, v184
	s_waitcnt vmcnt(2)
	v_add_f32_e32 v188, v188, v189
	v_add_f32_e32 v190, v190, v191
	v_add_f32_e32 v188, v188, v190
	ds_bpermute_b32 v189, v200, v188
	s_waitcnt vmcnt(1)
	v_add_f32_e32 v192, v192, v193
	v_add_f32_e32 v194, v194, v195
	v_add_f32_e32 v192, v192, v194
	ds_bpermute_b32 v193, v200, v192
	s_waitcnt vmcnt(0)
	v_add_f32_e32 v196, v196, v197
	v_add_f32_e32 v198, v198, v199
	v_add_f32_e32 v196, v196, v198
	ds_bpermute_b32 v197, v200, v196
	s_waitcnt lgkmcnt(7)
	v_add_f32_e32 v168, v168, v169
	ds_bpermute_b32 v169, v201, v168
	s_waitcnt lgkmcnt(7)
	v_add_f32_e32 v172, v172, v173
	ds_bpermute_b32 v173, v201, v172
	s_waitcnt lgkmcnt(7)
	v_add_f32_e32 v176, v176, v177
	ds_bpermute_b32 v177, v201, v176
	s_waitcnt lgkmcnt(7)
	v_add_f32_e32 v180, v180, v181
	ds_bpermute_b32 v181, v201, v180
	s_waitcnt lgkmcnt(7)
	v_add_f32_e32 v184, v184, v185
	ds_bpermute_b32 v185, v201, v184
	s_waitcnt lgkmcnt(7)
	v_add_f32_e32 v188, v188, v189
	ds_bpermute_b32 v189, v201, v188
	s_waitcnt lgkmcnt(7)
	v_add_f32_e32 v192, v192, v193
	ds_bpermute_b32 v193, v201, v192
	s_waitcnt lgkmcnt(7)
	v_add_f32_e32 v196, v196, v197
	ds_bpermute_b32 v197, v201, v196
	s_waitcnt lgkmcnt(7)
	v_add_f32_e32 v168, v168, v169
	v_fmamk_f32 v168, v168, 0x3a800000, v239
	s_waitcnt lgkmcnt(6)
	v_add_f32_e32 v172, v172, v173
	v_fmamk_f32 v172, v172, 0x3a800000, v239
	s_waitcnt lgkmcnt(5)
	v_add_f32_e32 v176, v176, v177
	v_fmamk_f32 v176, v176, 0x3a800000, v239
	s_waitcnt lgkmcnt(4)
	v_add_f32_e32 v180, v180, v181
	v_fmamk_f32 v180, v180, 0x3a800000, v239
	s_waitcnt lgkmcnt(3)
	v_add_f32_e32 v184, v184, v185
	v_fmamk_f32 v184, v184, 0x3a800000, v239
	s_waitcnt lgkmcnt(2)
	v_add_f32_e32 v188, v188, v189
	v_fmamk_f32 v188, v188, 0x3a800000, v239
	s_waitcnt lgkmcnt(1)
	v_add_f32_e32 v192, v192, v193
	v_fmamk_f32 v192, v192, 0x3a800000, v239
	s_waitcnt lgkmcnt(0)
	v_add_f32_e32 v196, v196, v197
	v_fmamk_f32 v196, v196, 0x3a800000, v239
	v_cmp_gt_f32_e32 vcc, s55, v168
	v_mul_f32_e32 v169, 0x4b800000, v168
	s_nop 0
	v_cndmask_b32_e32 v168, v168, v169, vcc
	v_rsq_f32_e32 v168, v168
	s_nop 0
	v_mul_f32_e32 v169, 0x45800000, v168
	v_cndmask_b32_e32 v164, v168, v169, vcc
	v_cmp_gt_f32_e32 vcc, s55, v172
	v_mul_f32_e32 v173, 0x4b800000, v172
	s_nop 0
	v_cndmask_b32_e32 v172, v172, v173, vcc
	v_rsq_f32_e32 v172, v172
	s_nop 0
	v_mul_f32_e32 v173, 0x45800000, v172
	v_cndmask_b32_e32 v163, v172, v173, vcc
	v_cmp_gt_f32_e32 vcc, s55, v176
	v_mul_f32_e32 v177, 0x4b800000, v176
	s_nop 0
	v_cndmask_b32_e32 v176, v176, v177, vcc
	v_rsq_f32_e32 v176, v176
	s_nop 0
	v_mul_f32_e32 v177, 0x45800000, v176
	v_cndmask_b32_e32 v162, v176, v177, vcc
	v_cmp_gt_f32_e32 vcc, s55, v180
	v_mul_f32_e32 v181, 0x4b800000, v180
	s_nop 0
	v_cndmask_b32_e32 v180, v180, v181, vcc
	v_rsq_f32_e32 v180, v180
	s_nop 0
	v_mul_f32_e32 v181, 0x45800000, v180
	v_cndmask_b32_e32 v161, v180, v181, vcc
	v_cmp_gt_f32_e32 vcc, s55, v184
	v_mul_f32_e32 v185, 0x4b800000, v184
	s_nop 0
	v_cndmask_b32_e32 v184, v184, v185, vcc
	v_rsq_f32_e32 v184, v184
	s_nop 0
	v_mul_f32_e32 v185, 0x45800000, v184
	v_cndmask_b32_e32 v160, v184, v185, vcc
	v_cmp_gt_f32_e32 vcc, s55, v188
	v_mul_f32_e32 v189, 0x4b800000, v188
	s_nop 0
	v_cndmask_b32_e32 v188, v188, v189, vcc
	v_rsq_f32_e32 v188, v188
	s_nop 0
	v_mul_f32_e32 v189, 0x45800000, v188
	v_cndmask_b32_e32 v155, v188, v189, vcc
	v_cmp_gt_f32_e32 vcc, s55, v192
	v_mul_f32_e32 v193, 0x4b800000, v192
	s_nop 0
	v_cndmask_b32_e32 v192, v192, v193, vcc
	v_rsq_f32_e32 v192, v192
	s_nop 0
	v_mul_f32_e32 v193, 0x45800000, v192
	v_cndmask_b32_e32 v153, v192, v193, vcc
	v_cmp_gt_f32_e32 vcc, s55, v196
	v_mul_f32_e32 v197, 0x4b800000, v196
	s_nop 0
	v_cndmask_b32_e32 v196, v196, v197, vcc
	v_rsq_f32_e32 v196, v196
	s_nop 0
	v_mul_f32_e32 v197, 0x45800000, v196
	v_cndmask_b32_e32 v151, v196, v197, vcc
.Lrsv_win_done:
.LBB0_347:
	s_lshl_b32 s21, s56, 8
	s_cmp_gt_i32 s56, 1
	s_cbranch_scc0 .LBB0_350
	s_lshl_b32 s4, s56, 1
	s_cmp_gt_u32 s4, 4
	s_cbranch_scc0 .LBB0_351
	s_cmp_gt_u32 s4, 13
	s_cselect_b64 vcc, -1, 0
	s_cmp_gt_u32 s4, 17
	s_cselect_b64 s[0:1], -1, 0
	s_cmp_gt_u32 s4, 25
	s_cselect_b64 s[6:7], -1, 0
	v_mov_b32_e32 v165, 0x3e38aa3b
	v_cndmask_b32_e64 v0, v165, 1.0, s[6:7]
	s_cmp_gt_u32 s4, 41
	v_cndmask_b32_e64 v0, 1.0, v0, s[0:1]
	s_cselect_b64 s[34:35], -1, 0
	v_cndmask_b32_e32 v165, v165, v0, vcc
	s_mov_b64 s[0:1], 0
	s_branch .LBB0_352
